# grid barrier: every WG polls the cross-XCD arrival counter (no release-generation hop), last local arriver elected by returning atomic, per-instance compile-time barrier index
# baseline (speedup 1.0000x reference)
; __device__ __forceinline__ unsigned xb_ld(unsigned* p)              { return __hip_atomic_load(p, __ATOMIC_RELAXED, __HIP_MEMORY_SCOPE_AGENT); }
; __device__ __forceinline__ unsigned xb_add(unsigned* p, unsigned v) { return __hip_atomic_fetch_add(p, v, __ATOMIC_RELAXED, __HIP_MEMORY_SCOPE_AGENT); }
; #define XB_SPIN(cond, bar) do { unsigned _sp = 0; while (cond) { __builtin_amdgcn_s_sleep(1); \
;     if ((++_sp & 255u) == 0u) { if (xb_ld(&(bar)[XB_TMO])) break; if (_sp > XB_SPIN_CAP) { atomicAdd(&(bar)[XB_TMO], 1u); break; } } } } while (0)
; __device__ __forceinline__ void xcd_barrier(const XcdBarrier& b) {
;     ...
;         unsigned nloc = b.st[0], nx = b.st[1];
;         if (nloc == 0u) { xcd_barrier_complete(bar, b.x, nloc, nx); b.st[0] = nloc; b.st[1] = nx; }
;         const unsigned old = xb_add(&bar[XB_XSUB(b.x)], 1u);
;         const unsigned gen = old / nloc;
;         if (old + 1u == (gen + 1u) * nloc) {
;             __builtin_amdgcn_fence(__ATOMIC_RELEASE, "agent");
;             asm volatile("s_waitcnt vmcnt(0)" ::: "memory");
;             const unsigned og = xb_add(&bar[XB_TOP], 1u);
;             const unsigned tg = og / nx;
;             if (og + 1u == (tg + 1u) * nx) xb_add(&bar[XB_TOPGEN], 1u);
;             else XB_SPIN(xb_ld(&bar[XB_TOPGEN]) == tg, bar);
;             __builtin_amdgcn_fence(__ATOMIC_ACQUIRE, "agent");
;             xb_add(&bar[XB_XGEN(b.x)], 1u);
;             asm volatile("s_waitcnt vmcnt(0)" ::: "memory");
;         } else {
;             XB_SPIN(xb_ld(&bar[XB_XGEN(b.x)]) == gen, bar);
;             __builtin_amdgcn_fence(__ATOMIC_ACQUIRE, "agent");
;             asm volatile("s_waitcnt vmcnt(0)" ::: "memory");
;         }
.LBB0_120:
	s_lshl_b32 s6, s3, 8
	s_add_u32 s6, s20, s6
	s_addc_u32 s7, s21, 0
	v_mov_b32_e32 v3, 1
	v_mov_b32_e32 v4, 0x1000
	global_atomic_add v3, v4, v3, s[6:7] offset:1024 sc0
	s_add_u32 s8, s58, 0x903400
	s_addc_u32 s9, s59, 0
	v_mov_b32_e32 v4, 0
	s_waitcnt lgkmcnt(0)
	v_mul_u32_u24_e32 v5, 1, v2
	v_mul_u32_u24_e32 v6, 1, v0
	s_waitcnt vmcnt(0)
	v_add_u32_e32 v3, 1, v3
	v_cmp_ne_u32_e32 vcc, v3, v5
	s_cbranch_vccnz .Lgbar_poll_0
	buffer_wbl2 sc1
	s_waitcnt vmcnt(0)
	v_mov_b32_e32 v3, 1
	global_atomic_add v4, v3, s[8:9]
.Lgbar_poll_0:
	v_mov_b32_e32 v5, 0
.Lgbar_loop_0:
	global_load_dword v3, v4, s[8:9] sc1
	s_waitcnt vmcnt(0)
	v_cmp_ge_u32_e32 vcc, v3, v6
	s_cbranch_vccnz .Lgbar_done_0
	s_sleep 1
	v_add_u32_e32 v5, 1, v5
	v_cmp_gt_u32_e32 vcc, 0x40000, v5
	s_cbranch_vccnz .Lgbar_loop_0
.Lgbar_done_0:
	buffer_inv sc1
	s_waitcnt vmcnt(0)

; __device__ __forceinline__ unsigned xb_ld(unsigned* p)              { return __hip_atomic_load(p, __ATOMIC_RELAXED, __HIP_MEMORY_SCOPE_AGENT); }
; __device__ __forceinline__ unsigned xb_add(unsigned* p, unsigned v) { return __hip_atomic_fetch_add(p, v, __ATOMIC_RELAXED, __HIP_MEMORY_SCOPE_AGENT); }
; #define XB_SPIN(cond, bar) do { unsigned _sp = 0; while (cond) { __builtin_amdgcn_s_sleep(1); \
;     if ((++_sp & 255u) == 0u) { if (xb_ld(&(bar)[XB_TMO])) break; if (_sp > XB_SPIN_CAP) { atomicAdd(&(bar)[XB_TMO], 1u); break; } } } } while (0)
; __device__ __forceinline__ void xcd_barrier(const XcdBarrier& b) {
;     ...
;         const unsigned old = xb_add(&bar[XB_XSUB(b.x)], 1u);
;         const unsigned gen = old / nloc;
;         if (old + 1u == (gen + 1u) * nloc) {
;             __builtin_amdgcn_fence(__ATOMIC_RELEASE, "agent");
;             asm volatile("s_waitcnt vmcnt(0)" ::: "memory");
;             const unsigned og = xb_add(&bar[XB_TOP], 1u);
;             const unsigned tg = og / nx;
;             if (og + 1u == (tg + 1u) * nx) xb_add(&bar[XB_TOPGEN], 1u);
;             else XB_SPIN(xb_ld(&bar[XB_TOPGEN]) == tg, bar);
.LBB0_185:
	v_readlane_b32 s4, v240, 0
	v_readlane_b32 s5, v240, 1
	v_mov_b32_e32 v3, 1
	v_mov_b32_e32 v4, 0
	s_nop 4
	global_atomic_add v3, v4, v3, s[4:5] sc0
	v_readlane_b32 s4, v240, 4
	v_readlane_b32 s5, v240, 5
	s_waitcnt lgkmcnt(0)
	v_mul_u32_u24_e32 v5, 2, v2
	v_mul_u32_u24_e32 v6, 2, v0
	s_waitcnt vmcnt(0)
	v_add_u32_e32 v3, 1, v3
	v_cmp_ne_u32_e32 vcc, v3, v5
	s_cbranch_vccnz .Lgbar_poll_1
	buffer_wbl2 sc1
	s_waitcnt vmcnt(0)
	v_mov_b32_e32 v3, 1
	global_atomic_add v4, v3, s[4:5]

; __device__ __forceinline__ unsigned xb_ld(unsigned* p)              { return __hip_atomic_load(p, __ATOMIC_RELAXED, __HIP_MEMORY_SCOPE_AGENT); }
; #define XB_SPIN(cond, bar) do { unsigned _sp = 0; while (cond) { __builtin_amdgcn_s_sleep(1); \
;     if ((++_sp & 255u) == 0u) { if (xb_ld(&(bar)[XB_TMO])) break; if (_sp > XB_SPIN_CAP) { atomicAdd(&(bar)[XB_TMO], 1u); break; } } } } while (0)
; __device__ __forceinline__ void xcd_barrier(const XcdBarrier& b) {
;     ...
;         } else {
;             XB_SPIN(xb_ld(&bar[XB_XGEN(b.x)]) == gen, bar);
;             __builtin_amdgcn_fence(__ATOMIC_ACQUIRE, "agent");
;             asm volatile("s_waitcnt vmcnt(0)" ::: "memory");
.Lgbar_loop_1:
	global_load_dword v3, v4, s[4:5] sc1
	s_waitcnt vmcnt(0)
	v_cmp_ge_u32_e32 vcc, v3, v6
	s_cbranch_vccnz .Lgbar_done_1
	s_sleep 1
	v_add_u32_e32 v5, 1, v5
	v_cmp_gt_u32_e32 vcc, 0x40000, v5
	s_cbranch_vccnz .Lgbar_loop_1

; __device__ __forceinline__ unsigned xb_ld(unsigned* p)              { return __hip_atomic_load(p, __ATOMIC_RELAXED, __HIP_MEMORY_SCOPE_AGENT); }
; __device__ __forceinline__ unsigned xb_add(unsigned* p, unsigned v) { return __hip_atomic_fetch_add(p, v, __ATOMIC_RELAXED, __HIP_MEMORY_SCOPE_AGENT); }
; #define XB_SPIN(cond, bar) do { unsigned _sp = 0; while (cond) { __builtin_amdgcn_s_sleep(1); \
;     if ((++_sp & 255u) == 0u) { if (xb_ld(&(bar)[XB_TMO])) break; if (_sp > XB_SPIN_CAP) { atomicAdd(&(bar)[XB_TMO], 1u); break; } } } } while (0)
; __device__ __forceinline__ void xcd_barrier(const XcdBarrier& b) {
;     ...
;         const unsigned old = xb_add(&bar[XB_XSUB(b.x)], 1u);
;         const unsigned gen = old / nloc;
;         if (old + 1u == (gen + 1u) * nloc) {
;             __builtin_amdgcn_fence(__ATOMIC_RELEASE, "agent");
;             asm volatile("s_waitcnt vmcnt(0)" ::: "memory");
;             const unsigned og = xb_add(&bar[XB_TOP], 1u);
;             const unsigned tg = og / nx;
;             if (og + 1u == (tg + 1u) * nx) xb_add(&bar[XB_TOPGEN], 1u);
;             else XB_SPIN(xb_ld(&bar[XB_TOPGEN]) == tg, bar);
.LBB0_261:
	v_readlane_b32 s4, v240, 0
	v_readlane_b32 s5, v240, 1
	v_mov_b32_e32 v3, 1
	v_mov_b32_e32 v4, 0
	s_nop 4
	global_atomic_add v3, v4, v3, s[4:5] sc0
	v_readlane_b32 s4, v240, 4
	v_readlane_b32 s5, v240, 5
	s_waitcnt lgkmcnt(0)
	v_mul_u32_u24_e32 v5, 3, v2
	v_mul_u32_u24_e32 v6, 3, v0
	s_waitcnt vmcnt(0)
	v_add_u32_e32 v3, 1, v3
	v_cmp_ne_u32_e32 vcc, v3, v5
	s_cbranch_vccnz .Lgbar_poll_2
	buffer_wbl2 sc1
	s_waitcnt vmcnt(0)
	v_mov_b32_e32 v3, 1
	global_atomic_add v4, v3, s[4:5]

; __device__ __forceinline__ unsigned xb_ld(unsigned* p)              { return __hip_atomic_load(p, __ATOMIC_RELAXED, __HIP_MEMORY_SCOPE_AGENT); }
; __device__ __forceinline__ unsigned xb_add(unsigned* p, unsigned v) { return __hip_atomic_fetch_add(p, v, __ATOMIC_RELAXED, __HIP_MEMORY_SCOPE_AGENT); }
; #define XB_SPIN(cond, bar) do { unsigned _sp = 0; while (cond) { __builtin_amdgcn_s_sleep(1); \
;     if ((++_sp & 255u) == 0u) { if (xb_ld(&(bar)[XB_TMO])) break; if (_sp > XB_SPIN_CAP) { atomicAdd(&(bar)[XB_TMO], 1u); break; } } } } while (0)
; __device__ __forceinline__ void xcd_barrier(const XcdBarrier& b) {
;     ...
;         const unsigned old = xb_add(&bar[XB_XSUB(b.x)], 1u);
;         const unsigned gen = old / nloc;
;         if (old + 1u == (gen + 1u) * nloc) {
;             __builtin_amdgcn_fence(__ATOMIC_RELEASE, "agent");
;             asm volatile("s_waitcnt vmcnt(0)" ::: "memory");
;             const unsigned og = xb_add(&bar[XB_TOP], 1u);
;             const unsigned tg = og / nx;
;             if (og + 1u == (tg + 1u) * nx) xb_add(&bar[XB_TOPGEN], 1u);
;             else XB_SPIN(xb_ld(&bar[XB_TOPGEN]) == tg, bar);
.LBB0_318:
	v_readlane_b32 s4, v240, 0
	v_readlane_b32 s5, v240, 1
	v_mov_b32_e32 v3, 1
	v_mov_b32_e32 v4, 0
	s_nop 4
	global_atomic_add v3, v4, v3, s[4:5] sc0
	v_readlane_b32 s4, v240, 4
	v_readlane_b32 s5, v240, 5
	s_waitcnt lgkmcnt(0)
	v_mul_u32_u24_e32 v5, 4, v2
	v_mul_u32_u24_e32 v6, 4, v0
	s_waitcnt vmcnt(0)
	v_add_u32_e32 v3, 1, v3
	v_cmp_ne_u32_e32 vcc, v3, v5
	s_cbranch_vccnz .Lgbar_poll_3
	buffer_wbl2 sc1
	s_waitcnt vmcnt(0)
	v_mov_b32_e32 v3, 1
	global_atomic_add v4, v3, s[4:5]

; __device__ __forceinline__ unsigned xb_ld(unsigned* p)              { return __hip_atomic_load(p, __ATOMIC_RELAXED, __HIP_MEMORY_SCOPE_AGENT); }
; __device__ __forceinline__ unsigned xb_add(unsigned* p, unsigned v) { return __hip_atomic_fetch_add(p, v, __ATOMIC_RELAXED, __HIP_MEMORY_SCOPE_AGENT); }
; #define XB_SPIN(cond, bar) do { unsigned _sp = 0; while (cond) { __builtin_amdgcn_s_sleep(1); \
;     if ((++_sp & 255u) == 0u) { if (xb_ld(&(bar)[XB_TMO])) break; if (_sp > XB_SPIN_CAP) { atomicAdd(&(bar)[XB_TMO], 1u); break; } } } } while (0)
; __device__ __forceinline__ void xcd_barrier(const XcdBarrier& b) {
;     ...
;         const unsigned old = xb_add(&bar[XB_XSUB(b.x)], 1u);
;         const unsigned gen = old / nloc;
;         if (old + 1u == (gen + 1u) * nloc) {
;             __builtin_amdgcn_fence(__ATOMIC_RELEASE, "agent");
;             asm volatile("s_waitcnt vmcnt(0)" ::: "memory");
;             const unsigned og = xb_add(&bar[XB_TOP], 1u);
;             const unsigned tg = og / nx;
;             if (og + 1u == (tg + 1u) * nx) xb_add(&bar[XB_TOPGEN], 1u);
;             else XB_SPIN(xb_ld(&bar[XB_TOPGEN]) == tg, bar);
.LBB0_446:
	v_readlane_b32 s4, v240, 0
	v_readlane_b32 s5, v240, 1
	v_mov_b32_e32 v3, 1
	v_mov_b32_e32 v4, 0
	s_nop 4
	global_atomic_add v3, v4, v3, s[4:5] sc0
	v_readlane_b32 s4, v240, 4
	v_readlane_b32 s5, v240, 5
	s_waitcnt lgkmcnt(0)
	v_mul_u32_u24_e32 v5, 5, v2
	v_mul_u32_u24_e32 v6, 5, v0
	s_waitcnt vmcnt(0)
	v_add_u32_e32 v3, 1, v3
	v_cmp_ne_u32_e32 vcc, v3, v5
	s_cbranch_vccnz .Lgbar_poll_4
	buffer_wbl2 sc1
	s_waitcnt vmcnt(0)
	v_mov_b32_e32 v3, 1
	global_atomic_add v4, v3, s[4:5]

; __device__ __forceinline__ unsigned xb_ld(unsigned* p)              { return __hip_atomic_load(p, __ATOMIC_RELAXED, __HIP_MEMORY_SCOPE_AGENT); }
; __device__ __forceinline__ unsigned xb_add(unsigned* p, unsigned v) { return __hip_atomic_fetch_add(p, v, __ATOMIC_RELAXED, __HIP_MEMORY_SCOPE_AGENT); }
; #define XB_SPIN(cond, bar) do { unsigned _sp = 0; while (cond) { __builtin_amdgcn_s_sleep(1); \
;     if ((++_sp & 255u) == 0u) { if (xb_ld(&(bar)[XB_TMO])) break; if (_sp > XB_SPIN_CAP) { atomicAdd(&(bar)[XB_TMO], 1u); break; } } } } while (0)
; __device__ __forceinline__ void xcd_barrier(const XcdBarrier& b) {
;     ...
;         const unsigned old = xb_add(&bar[XB_XSUB(b.x)], 1u);
;         const unsigned gen = old / nloc;
;         if (old + 1u == (gen + 1u) * nloc) {
;             __builtin_amdgcn_fence(__ATOMIC_RELEASE, "agent");
;             asm volatile("s_waitcnt vmcnt(0)" ::: "memory");
;             const unsigned og = xb_add(&bar[XB_TOP], 1u);
;             const unsigned tg = og / nx;
;             if (og + 1u == (tg + 1u) * nx) xb_add(&bar[XB_TOPGEN], 1u);
;             else XB_SPIN(xb_ld(&bar[XB_TOPGEN]) == tg, bar);
.LBB0_503:
	v_readlane_b32 s4, v240, 0
	v_readlane_b32 s5, v240, 1
	v_mov_b32_e32 v3, 1
	v_mov_b32_e32 v4, 0
	s_nop 4
	global_atomic_add v3, v4, v3, s[4:5] sc0
	v_readlane_b32 s4, v240, 4
	v_readlane_b32 s5, v240, 5
	s_waitcnt lgkmcnt(0)
	v_mul_u32_u24_e32 v5, 6, v2
	v_mul_u32_u24_e32 v6, 6, v0
	s_waitcnt vmcnt(0)
	v_add_u32_e32 v3, 1, v3
	v_cmp_ne_u32_e32 vcc, v3, v5
	s_cbranch_vccnz .Lgbar_poll_5
	buffer_wbl2 sc1
	s_waitcnt vmcnt(0)
	v_mov_b32_e32 v3, 1
	global_atomic_add v4, v3, s[4:5]

; __device__ __forceinline__ unsigned xb_ld(unsigned* p)              { return __hip_atomic_load(p, __ATOMIC_RELAXED, __HIP_MEMORY_SCOPE_AGENT); }
; __device__ __forceinline__ unsigned xb_add(unsigned* p, unsigned v) { return __hip_atomic_fetch_add(p, v, __ATOMIC_RELAXED, __HIP_MEMORY_SCOPE_AGENT); }
; #define XB_SPIN(cond, bar) do { unsigned _sp = 0; while (cond) { __builtin_amdgcn_s_sleep(1); \
;     if ((++_sp & 255u) == 0u) { if (xb_ld(&(bar)[XB_TMO])) break; if (_sp > XB_SPIN_CAP) { atomicAdd(&(bar)[XB_TMO], 1u); break; } } } } while (0)
; __device__ __forceinline__ void xcd_barrier(const XcdBarrier& b) {
;     ...
;         const unsigned old = xb_add(&bar[XB_XSUB(b.x)], 1u);
;         const unsigned gen = old / nloc;
;         if (old + 1u == (gen + 1u) * nloc) {
;             __builtin_amdgcn_fence(__ATOMIC_RELEASE, "agent");
;             asm volatile("s_waitcnt vmcnt(0)" ::: "memory");
;             const unsigned og = xb_add(&bar[XB_TOP], 1u);
;             const unsigned tg = og / nx;
;             if (og + 1u == (tg + 1u) * nx) xb_add(&bar[XB_TOPGEN], 1u);
;             else XB_SPIN(xb_ld(&bar[XB_TOPGEN]) == tg, bar);
.LBB0_679:
	v_readlane_b32 s4, v240, 0
	v_readlane_b32 s5, v240, 1
	v_mov_b32_e32 v3, 1
	v_mov_b32_e32 v4, 0
	s_nop 4
	global_atomic_add v3, v4, v3, s[4:5] sc0
	v_readlane_b32 s4, v240, 4
	v_readlane_b32 s5, v240, 5
	s_waitcnt lgkmcnt(0)
	v_mul_u32_u24_e32 v5, 7, v2
	v_mul_u32_u24_e32 v6, 7, v0
	s_waitcnt vmcnt(0)
	v_add_u32_e32 v3, 1, v3
	v_cmp_ne_u32_e32 vcc, v3, v5
	s_cbranch_vccnz .Lgbar_poll_6
	buffer_wbl2 sc1
	s_waitcnt vmcnt(0)
	v_mov_b32_e32 v3, 1
	global_atomic_add v4, v3, s[4:5]

; __device__ __forceinline__ unsigned xb_ld(unsigned* p)              { return __hip_atomic_load(p, __ATOMIC_RELAXED, __HIP_MEMORY_SCOPE_AGENT); }
; __device__ __forceinline__ unsigned xb_add(unsigned* p, unsigned v) { return __hip_atomic_fetch_add(p, v, __ATOMIC_RELAXED, __HIP_MEMORY_SCOPE_AGENT); }
; #define XB_SPIN(cond, bar) do { unsigned _sp = 0; while (cond) { __builtin_amdgcn_s_sleep(1); \
;     if ((++_sp & 255u) == 0u) { if (xb_ld(&(bar)[XB_TMO])) break; if (_sp > XB_SPIN_CAP) { atomicAdd(&(bar)[XB_TMO], 1u); break; } } } } while (0)
; __device__ __forceinline__ void xcd_barrier(const XcdBarrier& b) {
;     ...
;         const unsigned old = xb_add(&bar[XB_XSUB(b.x)], 1u);
;         const unsigned gen = old / nloc;
;         if (old + 1u == (gen + 1u) * nloc) {
;             __builtin_amdgcn_fence(__ATOMIC_RELEASE, "agent");
;             asm volatile("s_waitcnt vmcnt(0)" ::: "memory");
;             const unsigned og = xb_add(&bar[XB_TOP], 1u);
;             const unsigned tg = og / nx;
;             if (og + 1u == (tg + 1u) * nx) xb_add(&bar[XB_TOPGEN], 1u);
;             else XB_SPIN(xb_ld(&bar[XB_TOPGEN]) == tg, bar);
.LBB0_755:
	v_readlane_b32 s4, v240, 0
	v_readlane_b32 s5, v240, 1
	v_mov_b32_e32 v3, 1
	v_mov_b32_e32 v4, 0
	s_nop 4
	global_atomic_add v3, v4, v3, s[4:5] sc0
	v_readlane_b32 s4, v240, 4
	v_readlane_b32 s5, v240, 5
	s_waitcnt lgkmcnt(0)
	v_mul_u32_u24_e32 v5, 8, v2
	v_mul_u32_u24_e32 v6, 8, v0
	s_waitcnt vmcnt(0)
	v_add_u32_e32 v3, 1, v3
	v_cmp_ne_u32_e32 vcc, v3, v5
	s_cbranch_vccnz .Lgbar_poll_7
	buffer_wbl2 sc1
	s_waitcnt vmcnt(0)
	v_mov_b32_e32 v3, 1
	global_atomic_add v4, v3, s[4:5]

; __device__ __forceinline__ unsigned xb_ld(unsigned* p)              { return __hip_atomic_load(p, __ATOMIC_RELAXED, __HIP_MEMORY_SCOPE_AGENT); }
; __device__ __forceinline__ unsigned xb_add(unsigned* p, unsigned v) { return __hip_atomic_fetch_add(p, v, __ATOMIC_RELAXED, __HIP_MEMORY_SCOPE_AGENT); }
; #define XB_SPIN(cond, bar) do { unsigned _sp = 0; while (cond) { __builtin_amdgcn_s_sleep(1); \
;     if ((++_sp & 255u) == 0u) { if (xb_ld(&(bar)[XB_TMO])) break; if (_sp > XB_SPIN_CAP) { atomicAdd(&(bar)[XB_TMO], 1u); break; } } } } while (0)
; __device__ __forceinline__ void xcd_barrier(const XcdBarrier& b) {
;     ...
;         const unsigned old = xb_add(&bar[XB_XSUB(b.x)], 1u);
;         const unsigned gen = old / nloc;
;         if (old + 1u == (gen + 1u) * nloc) {
;             __builtin_amdgcn_fence(__ATOMIC_RELEASE, "agent");
;             asm volatile("s_waitcnt vmcnt(0)" ::: "memory");
;             const unsigned og = xb_add(&bar[XB_TOP], 1u);
;             const unsigned tg = og / nx;
;             if (og + 1u == (tg + 1u) * nx) xb_add(&bar[XB_TOPGEN], 1u);
;             else XB_SPIN(xb_ld(&bar[XB_TOPGEN]) == tg, bar);
.LBB0_820:
	v_readlane_b32 s4, v240, 0
	v_readlane_b32 s5, v240, 1
	v_mov_b32_e32 v3, 1
	v_mov_b32_e32 v4, 0
	s_nop 4
	global_atomic_add v3, v4, v3, s[4:5] sc0
	v_readlane_b32 s4, v240, 4
	v_readlane_b32 s5, v240, 5
	s_waitcnt lgkmcnt(0)
	v_mul_u32_u24_e32 v5, 9, v2
	v_mul_u32_u24_e32 v6, 9, v0
	s_waitcnt vmcnt(0)
	v_add_u32_e32 v3, 1, v3
	v_cmp_ne_u32_e32 vcc, v3, v5
	s_cbranch_vccnz .Lgbar_poll_8
	buffer_wbl2 sc1
	s_waitcnt vmcnt(0)
	v_mov_b32_e32 v3, 1
	global_atomic_add v4, v3, s[4:5]

; __device__ __forceinline__ unsigned xb_ld(unsigned* p)              { return __hip_atomic_load(p, __ATOMIC_RELAXED, __HIP_MEMORY_SCOPE_AGENT); }
; __device__ __forceinline__ unsigned xb_add(unsigned* p, unsigned v) { return __hip_atomic_fetch_add(p, v, __ATOMIC_RELAXED, __HIP_MEMORY_SCOPE_AGENT); }
; #define XB_SPIN(cond, bar) do { unsigned _sp = 0; while (cond) { __builtin_amdgcn_s_sleep(1); \
;     if ((++_sp & 255u) == 0u) { if (xb_ld(&(bar)[XB_TMO])) break; if (_sp > XB_SPIN_CAP) { atomicAdd(&(bar)[XB_TMO], 1u); break; } } } } while (0)
; __device__ __forceinline__ void xcd_barrier(const XcdBarrier& b) {
;     ...
;         const unsigned old = xb_add(&bar[XB_XSUB(b.x)], 1u);
;         const unsigned gen = old / nloc;
;         if (old + 1u == (gen + 1u) * nloc) {
;             __builtin_amdgcn_fence(__ATOMIC_RELEASE, "agent");
;             asm volatile("s_waitcnt vmcnt(0)" ::: "memory");
;             const unsigned og = xb_add(&bar[XB_TOP], 1u);
;             const unsigned tg = og / nx;
;             if (og + 1u == (tg + 1u) * nx) xb_add(&bar[XB_TOPGEN], 1u);
;             else XB_SPIN(xb_ld(&bar[XB_TOPGEN]) == tg, bar);
.LBB0_889:
	v_readlane_b32 s4, v240, 0
	v_readlane_b32 s5, v240, 1
	v_mov_b32_e32 v3, 1
	v_mov_b32_e32 v4, 0
	s_nop 4
	global_atomic_add v3, v4, v3, s[4:5] sc0
	v_readlane_b32 s4, v240, 4
	v_readlane_b32 s5, v240, 5
	s_waitcnt lgkmcnt(0)
	v_mul_u32_u24_e32 v5, 10, v2
	v_mul_u32_u24_e32 v6, 10, v0
	s_waitcnt vmcnt(0)
	v_add_u32_e32 v3, 1, v3
	v_cmp_ne_u32_e32 vcc, v3, v5
	s_cbranch_vccnz .Lgbar_poll_9
	buffer_wbl2 sc1
	s_waitcnt vmcnt(0)
	v_mov_b32_e32 v3, 1
	global_atomic_add v4, v3, s[4:5]

; __device__ __forceinline__ unsigned xb_ld(unsigned* p)              { return __hip_atomic_load(p, __ATOMIC_RELAXED, __HIP_MEMORY_SCOPE_AGENT); }
; __device__ __forceinline__ unsigned xb_add(unsigned* p, unsigned v) { return __hip_atomic_fetch_add(p, v, __ATOMIC_RELAXED, __HIP_MEMORY_SCOPE_AGENT); }
; #define XB_SPIN(cond, bar) do { unsigned _sp = 0; while (cond) { __builtin_amdgcn_s_sleep(1); \
;     if ((++_sp & 255u) == 0u) { if (xb_ld(&(bar)[XB_TMO])) break; if (_sp > XB_SPIN_CAP) { atomicAdd(&(bar)[XB_TMO], 1u); break; } } } } while (0)
; __device__ __forceinline__ void xcd_barrier(const XcdBarrier& b) {
;     ...
;         const unsigned old = xb_add(&bar[XB_XSUB(b.x)], 1u);
;         const unsigned gen = old / nloc;
;         if (old + 1u == (gen + 1u) * nloc) {
;             __builtin_amdgcn_fence(__ATOMIC_RELEASE, "agent");
;             asm volatile("s_waitcnt vmcnt(0)" ::: "memory");
;             const unsigned og = xb_add(&bar[XB_TOP], 1u);
;             const unsigned tg = og / nx;
;             if (og + 1u == (tg + 1u) * nx) xb_add(&bar[XB_TOPGEN], 1u);
;             else XB_SPIN(xb_ld(&bar[XB_TOPGEN]) == tg, bar);
.LBB0_969:
	v_readlane_b32 s4, v240, 0
	v_readlane_b32 s5, v240, 1
	v_mov_b32_e32 v3, 1
	v_mov_b32_e32 v4, 0
	s_nop 4
	global_atomic_add v3, v4, v3, s[4:5] sc0
	v_readlane_b32 s4, v240, 4
	v_readlane_b32 s5, v240, 5
	s_waitcnt lgkmcnt(0)
	v_mul_u32_u24_e32 v5, 11, v2
	v_mul_u32_u24_e32 v6, 11, v0
	s_waitcnt vmcnt(0)
	v_add_u32_e32 v3, 1, v3
	v_cmp_ne_u32_e32 vcc, v3, v5
	s_cbranch_vccnz .Lgbar_poll_10
	buffer_wbl2 sc1
	s_waitcnt vmcnt(0)
	v_mov_b32_e32 v3, 1
	global_atomic_add v4, v3, s[4:5]
